# stacked: flat seam counters + EVIN-tail GEMV rolling pipeline + EVENA chunk-state next-item prefetch
# speedup vs baseline: 1.0030x; 1.0030x over previous
.LBB0_462:
	s_cmpk_gt_i32 s4, 0x3ff
	s_cbranch_scc1 .LBB0_465
	v_ashrrev_i32_e32 v38, 3, v53
	v_and_b32_e32 v0, 56, v72
	v_sub_u32_e32 v2, 63, v38
	v_lshlrev_b32_e32 v168, 3, v0
	v_cvt_f32_i32_e32 v39, v2
	v_lshl_add_u64 v[2:3], s[10:11], 0, v[168:169]
	s_mov_b64 s[12:13], 0x100000
	s_ashr_i32 s5, s5, 6
	v_lshl_add_u64 v[32:33], v[2:3], 0, s[12:13]
	s_movk_i32 s12, 0x110
	v_mul_lo_u32 v2, v38, s12
	s_lshl_b32 s12, s5, 5
	v_lshlrev_b32_e32 v3, 1, v0
	s_and_b32 s13, s12, 0x60
	v_add3_u32 v40, 0, v2, v3
	s_lshl_b32 s5, s5, 4
	s_lshl_b32 s12, s13, 1
	v_lshlrev_b32_e32 v2, 1, v53
	s_and_b32 s14, s5, 0xffffffc0
	s_add_i32 s12, s12, 0
	v_and_b32_e32 v4, 62, v2
	v_add_u32_e32 v5, s12, v4
	s_lshl_b32 s12, s14, 1
	s_add_i32 s12, s12, 0
	v_bfi_b32 v2, 63, v53, s5
	s_ashr_i32 s15, s14, 31
	s_ashr_i32 s5, s4, 31
	v_bfe_u32 v1, v53, 5, 1
	v_add_u32_e32 v6, s12, v4
	s_lshl_b32 s12, s4, 4
	s_lshl_b64 s[16:17], s[4:5], 15
	s_lshl_b64 s[14:15], s[14:15], 1
	v_mul_u32_u24_e32 v8, 0x880, v1
	s_add_u32 s14, s16, s14
	v_lshlrev_b32_e32 v1, 10, v1
	v_lshl_or_b32 v2, v2, 1, 64
	s_addc_u32 s15, s17, s15
	v_lshl_or_b32 v168, s13, 8, v1
	v_add_u32_e32 v7, 0, v2
	v_lshl_add_u64 v[2:3], s[14:15], 0, v[168:169]
	v_or_b32_e32 v2, v2, v4
	v_lshl_add_u64 v[2:3], s[10:11], 0, v[2:3]
	s_mov_b64 s[10:11], 0x11701b40
	v_lshl_add_u64 v[34:35], v[2:3], 0, s[10:11]
	v_lshlrev_b32_e32 v168, 1, v0
	v_add_u32_e32 v41, v5, v8
	v_add_u32_e32 v42, v6, v8
	v_add_u32_e32 v43, v7, v8
	s_and_b32 s13, s12, 0xfc0
	s_and_b32 s14, s12, 0xffffffc0
	s_and_b32 s26, s4, 3
	s_lshl_b32 s26, s26, 8
	v_mov_b64_e32 v[110:111], s[6:7]
	v_add_u32_e32 v113, s14, v38
	v_add_u32_e32 v112, s13, v38
	v_mad_i64_i32 v[110:111], s[14:15], v113, s85, v[110:111]
	v_ashrrev_i32_e32 v113, 31, v112
	v_lshl_add_u64 v[110:111], v[110:111], 0, s[26:27]
	v_lshlrev_b64 v[112:113], 9, v[112:113]
	v_lshl_add_u64 v[116:117], v[110:111], 0, v[168:169]
	v_lshl_add_u64 v[114:115], v[32:33], 0, v[112:113]
	s_mov_b64 s[14:15], 0x1000
	global_load_dwordx4 v[120:123], v[114:115], off
	global_load_dwordx4 v[124:127], v[114:115], off offset:16
	global_load_dwordx4 v[128:131], v[114:115], off offset:48
	global_load_dwordx4 v[132:135], v[114:115], off offset:32
	v_lshl_add_u64 v[118:119], v[116:117], 0, s[14:15]
	global_load_dwordx4 v[136:139], v[118:119], off
	global_load_dwordx4 v[140:143], v[118:119], off offset:128
	global_load_dwordx4 v[144:147], v[118:119], off offset:1024
	global_load_dwordx4 v[148:151], v[118:119], off offset:1152
	s_waitcnt vmcnt(0)
.LBB0_464:
	s_and_b32 s5, s4, 3
	s_getpc_b64 s[10:11]
	s_add_u32 s10, s10, _ZN2mk5LOG2GE@rel32@lo+4
	s_addc_u32 s11, s11, _ZN2mk5LOG2GE@rel32@hi+12
	s_movk_i32 s15, 0xf000
	s_lshl_b32 s5, s5, 2
	v_add_co_u32_e32 v36, vcc, s15, v34
	s_load_dword s5, s[10:11], s5 offset:0x0
	v_addc_co_u32_e32 v37, vcc, -1, v35, vcc
	s_waitcnt vmcnt(32)
	v_mov_b32_e32 v0, v120
	v_mov_b32_e32 v1, v121
	v_mov_b32_e32 v2, v122
	v_mov_b32_e32 v3, v123
	v_mov_b32_e32 v4, v124
	v_mov_b32_e32 v5, v125
	v_mov_b32_e32 v6, v126
	v_mov_b32_e32 v7, v127
	v_mov_b32_e32 v8, v128
	v_mov_b32_e32 v9, v129
	v_mov_b32_e32 v10, v130
	v_mov_b32_e32 v11, v131
	v_mov_b32_e32 v12, v132
	v_mov_b32_e32 v13, v133
	v_mov_b32_e32 v14, v134
	v_mov_b32_e32 v15, v135
	v_mov_b32_e32 v16, v136
	v_mov_b32_e32 v17, v137
	v_mov_b32_e32 v18, v138
	v_mov_b32_e32 v19, v139
	v_mov_b32_e32 v20, v140
	v_mov_b32_e32 v21, v141
	v_mov_b32_e32 v22, v142
	v_mov_b32_e32 v23, v143
	v_mov_b32_e32 v24, v144
	v_mov_b32_e32 v25, v145
	v_mov_b32_e32 v26, v146
	v_mov_b32_e32 v27, v147
	v_mov_b32_e32 v28, v148
	v_mov_b32_e32 v29, v149
	v_mov_b32_e32 v30, v150
	v_mov_b32_e32 v31, v151
	s_add_i32 s4, s4, s24
	s_add_i32 s12, s12, s76
	s_cmpk_lt_i32 s4, 0x400
	s_cselect_b32 s16, 1, 0
	s_cbranch_scc0 .Levena_nopf
	s_and_b32 s13, s12, 0xfc0
	s_and_b32 s14, s12, 0xffffffc0
	s_and_b32 s26, s4, 3
	s_lshl_b32 s26, s26, 8
	v_mov_b64_e32 v[110:111], s[6:7]
	v_add_u32_e32 v113, s14, v38
	v_add_u32_e32 v112, s13, v38
	v_mad_i64_i32 v[110:111], s[14:15], v113, s85, v[110:111]
	v_ashrrev_i32_e32 v113, 31, v112
	v_lshl_add_u64 v[110:111], v[110:111], 0, s[26:27]
	v_lshlrev_b64 v[112:113], 9, v[112:113]
	v_lshl_add_u64 v[116:117], v[110:111], 0, v[168:169]
	v_lshl_add_u64 v[114:115], v[32:33], 0, v[112:113]
	s_mov_b64 s[14:15], 0x1000
	global_load_dwordx4 v[120:123], v[114:115], off
	global_load_dwordx4 v[124:127], v[114:115], off offset:16
	global_load_dwordx4 v[128:131], v[114:115], off offset:48
	global_load_dwordx4 v[132:135], v[114:115], off offset:32
	v_lshl_add_u64 v[118:119], v[116:117], 0, s[14:15]
	global_load_dwordx4 v[136:139], v[118:119], off
	global_load_dwordx4 v[140:143], v[118:119], off offset:128
	global_load_dwordx4 v[144:147], v[118:119], off offset:1024
	global_load_dwordx4 v[148:151], v[118:119], off offset:1152
.Levena_nopf:
	s_waitcnt lgkmcnt(0)
	v_mul_f32_e32 v44, s5, v39
	v_exp_f32_e32 v44, v44
	s_nop 0
	v_mul_f32_e32 v44, 0x3db504f3, v44
	ds_write_b128 v40, v[24:27] offset:17408
	ds_write_b128 v40, v[28:31] offset:17536
	v_mov_b32_e32 v46, v0
	v_mov_b32_e32 v47, v2
	v_mov_b32_e32 v2, v1
	v_mov_b32_e32 v0, v4
	v_mov_b32_e32 v1, v6
	v_mov_b32_e32 v6, v5
	v_mov_b32_e32 v4, v12
	v_mov_b32_e32 v5, v14
	v_mov_b32_e32 v14, v13
	v_mov_b32_e32 v13, v10
	v_mov_b32_e32 v10, v9
	v_lshlrev_b32_e32 v48, 16, v20
	v_and_b32_e32 v49, 0xffff0000, v20
	v_lshlrev_b32_e32 v20, 16, v21
	v_and_b32_e32 v21, 0xffff0000, v21
	v_lshlrev_b32_e32 v52, 16, v22
	v_and_b32_e32 v53, 0xffff0000, v22
	v_lshlrev_b32_e32 v22, 16, v23
	v_and_b32_e32 v23, 0xffff0000, v23
	v_mov_b32_e32 v12, v8
	v_lshlrev_b32_e32 v8, 16, v16
	v_and_b32_e32 v9, 0xffff0000, v16
	v_lshlrev_b32_e32 v16, 16, v17
	v_and_b32_e32 v17, 0xffff0000, v17
	v_lshlrev_b32_e32 v50, 16, v18
	v_and_b32_e32 v51, 0xffff0000, v18
	v_lshlrev_b32_e32 v18, 16, v19
	v_and_b32_e32 v19, 0xffff0000, v19
	v_pk_mul_f32 v[24:25], v[2:3], v[48:49]
	v_pk_mul_f32 v[26:27], v[46:47], v[48:49]
	v_pk_mul_f32 v[28:29], v[6:7], v[20:21]
	v_pk_mul_f32 v[30:31], v[14:15], v[52:53]
	v_pk_mul_f32 v[48:49], v[4:5], v[52:53]
	v_pk_mul_f32 v[52:53], v[10:11], v[22:23]
	v_pk_mul_f32 v[20:21], v[0:1], v[20:21]
	v_pk_mul_f32 v[22:23], v[12:13], v[22:23]
	v_pk_fma_f32 v[24:25], v[46:47], v[8:9], v[24:25] neg_lo:[0,0,1] neg_hi:[0,0,1]
	v_pk_fma_f32 v[2:3], v[2:3], v[8:9], v[26:27]
	v_pk_fma_f32 v[0:1], v[0:1], v[16:17], v[28:29] neg_lo:[0,0,1] neg_hi:[0,0,1]
	v_pk_fma_f32 v[4:5], v[4:5], v[50:51], v[30:31] neg_lo:[0,0,1] neg_hi:[0,0,1]
	v_pk_fma_f32 v[12:13], v[12:13], v[18:19], v[52:53] neg_lo:[0,0,1] neg_hi:[0,0,1]
	v_pk_fma_f32 v[6:7], v[6:7], v[16:17], v[20:21]
	v_pk_fma_f32 v[8:9], v[14:15], v[50:51], v[48:49]
	v_pk_fma_f32 v[10:11], v[10:11], v[18:19], v[22:23]
	v_pk_mul_f32 v[14:15], v[44:45], v[24:25] op_sel_hi:[0,1]
	v_pk_mul_f32 v[2:3], v[44:45], v[2:3] op_sel_hi:[0,1]
	v_pk_mul_f32 v[16:17], v[44:45], v[0:1] op_sel_hi:[0,1]
	v_pk_mul_f32 v[18:19], v[44:45], v[4:5] op_sel_hi:[0,1]
	v_pk_mul_f32 v[12:13], v[44:45], v[12:13] op_sel_hi:[0,1]
	v_pk_mul_f32 v[6:7], v[44:45], v[6:7] op_sel_hi:[0,1]
	v_pk_mul_f32 v[8:9], v[44:45], v[8:9] op_sel_hi:[0,1]
	v_pk_mul_f32 v[10:11], v[44:45], v[10:11] op_sel_hi:[0,1]
	v_cvt_pk_bf16_f32 v0, v14, v15
	v_cvt_pk_bf16_f32 v4, v2, v3
	v_cvt_pk_bf16_f32 v1, v16, v17
	v_cvt_pk_bf16_f32 v2, v18, v19
	v_cvt_pk_bf16_f32 v3, v12, v13
	v_cvt_pk_bf16_f32 v5, v6, v7
	v_cvt_pk_bf16_f32 v6, v8, v9
	v_cvt_pk_bf16_f32 v7, v10, v11
	ds_write_b128 v40, v[0:3]
	ds_write_b128 v40, v[4:7] offset:128
	s_waitcnt lgkmcnt(0)
	s_barrier
	ds_read_u16 v0, v41 offset:17408
	ds_read_u16 v1, v41 offset:17680
	ds_read_u16 v2, v41 offset:17952
	ds_read_u16 v3, v41 offset:18224
	ds_read_u16 v4, v41 offset:18496
	ds_read_u16 v5, v41 offset:18768
	ds_read_u16 v6, v41 offset:19040
	ds_read_u16 v7, v41 offset:19312
	ds_read_u16 v8, v42
	ds_read_u16 v9, v42 offset:272
	ds_read_u16 v10, v42 offset:544
	ds_read_u16 v11, v42 offset:816
	ds_read_u16 v12, v42 offset:1088
	ds_read_u16 v13, v42 offset:1360
	ds_read_u16 v14, v42 offset:1632
	ds_read_u16 v15, v42 offset:1904
	ds_read_u16 v20, v43
	ds_read_u16 v21, v43 offset:272
	ds_read_u16 v22, v43 offset:544
	ds_read_u16 v23, v43 offset:816
	ds_read_u16 v24, v43 offset:1088
	ds_read_u16 v25, v43 offset:1360
	ds_read_u16 v26, v43 offset:1632
	ds_read_u16 v27, v43 offset:1904
	ds_read_u16 v28, v41 offset:21760
	ds_read_u16 v29, v41 offset:22032
	ds_read_u16 v45, v41 offset:22304
	ds_read_u16 v46, v41 offset:22576
	ds_read_u16 v47, v41 offset:22848
	ds_read_u16 v48, v41 offset:23120
	ds_read_u16 v49, v41 offset:23392
	ds_read_u16 v50, v41 offset:23664
	ds_read_u16 v51, v42 offset:4352
	ds_read_u16 v52, v42 offset:4624
	ds_read_u16 v53, v42 offset:4896
	ds_read_u16 v54, v42 offset:5168
	ds_read_u16 v55, v42 offset:5440
	ds_read_u16 v56, v42 offset:5712
	ds_read_u16 v57, v42 offset:5984
	ds_read_u16 v58, v42 offset:6256
	ds_read_u16 v59, v43 offset:4352
	ds_read_u16 v60, v43 offset:4624
	ds_read_u16 v61, v43 offset:4896
	ds_read_u16 v62, v43 offset:5168
	ds_read_u16 v63, v43 offset:5440
	ds_read_u16 v64, v43 offset:5712
	ds_read_u16 v65, v43 offset:5984
	ds_read_u16 v66, v43 offset:6256
	ds_read_u16 v67, v41 offset:26112
	ds_read_u16 v68, v41 offset:26384
	ds_read_u16 v69, v41 offset:26656
	ds_read_u16 v70, v41 offset:26928
	ds_read_u16 v71, v41 offset:27200
	ds_read_u16 v72, v41 offset:27472
	ds_read_u16 v73, v41 offset:27744
	ds_read_u16 v74, v41 offset:28016
	ds_read_u16 v75, v42 offset:8704
	ds_read_u16 v76, v42 offset:8976
	ds_read_u16 v77, v42 offset:9248
	ds_read_u16 v78, v42 offset:9520
	ds_read_u16 v79, v42 offset:9792
	ds_read_u16 v80, v42 offset:10064
	ds_read_u16 v81, v42 offset:10336
	ds_read_u16 v82, v42 offset:10608
	ds_read_u16 v83, v43 offset:8704
	ds_read_u16 v84, v43 offset:8976
	ds_read_u16 v85, v43 offset:9248
	ds_read_u16 v86, v43 offset:9520
	ds_read_u16 v87, v43 offset:9792
	ds_read_u16 v88, v43 offset:10064
	ds_read_u16 v89, v43 offset:10336
	ds_read_u16 v90, v43 offset:10608
	ds_read_u16 v91, v41 offset:30464
	ds_read_u16 v92, v41 offset:30736
	ds_read_u16 v93, v41 offset:31008
	ds_read_u16 v94, v41 offset:31280
	ds_read_u16 v95, v41 offset:31552
	ds_read_u16 v96, v41 offset:31824
	ds_read_u16 v97, v41 offset:32096
	ds_read_u16 v98, v41 offset:32368
	ds_read_u16 v99, v42 offset:13056
	ds_read_u16 v100, v42 offset:13328
	ds_read_u16 v101, v42 offset:13600
	ds_read_u16 v102, v42 offset:13872
	ds_read_u16 v103, v42 offset:14144
	ds_read_u16 v104, v42 offset:14416
	ds_read_u16 v105, v42 offset:14688
	ds_read_u16 v106, v42 offset:14960
	s_waitcnt lgkmcnt(14)
	v_lshl_or_b32 v16, v1, 16, v0
	v_lshl_or_b32 v17, v3, 16, v2
	v_lshl_or_b32 v18, v5, 16, v4
	v_lshl_or_b32 v19, v7, 16, v6
	v_lshl_or_b32 v0, v9, 16, v8
	v_lshl_or_b32 v1, v11, 16, v10
	v_lshl_or_b32 v2, v13, 16, v12
	v_lshl_or_b32 v3, v15, 16, v14
	v_lshl_or_b32 v44, v29, 16, v28
	v_lshl_or_b32 v45, v46, 16, v45
	v_mfma_f32_32x32x16_bf16 v[0:15], v[16:19], v[0:3], 0
	v_lshl_or_b32 v46, v48, 16, v47
	v_lshl_or_b32 v47, v50, 16, v49
	v_lshl_or_b32 v20, v21, 16, v20
	v_lshl_or_b32 v21, v23, 16, v22
	v_lshl_or_b32 v22, v25, 16, v24
	v_lshl_or_b32 v23, v27, 16, v26
	v_lshl_or_b32 v48, v52, 16, v51
	v_lshl_or_b32 v49, v54, 16, v53
	v_mfma_f32_32x32x16_bf16 v[16:31], v[16:19], v[20:23], 0
	v_lshl_or_b32 v50, v56, 16, v55
	v_lshl_or_b32 v51, v58, 16, v57
	v_lshl_or_b32 v52, v68, 16, v67
	v_lshl_or_b32 v53, v70, 16, v69
	v_lshl_or_b32 v54, v72, 16, v71
	v_lshl_or_b32 v55, v74, 16, v73
	ds_read_u16 v107, v43 offset:13056
	ds_read_u16 v108, v43 offset:13328
	v_mfma_f32_32x32x16_bf16 v[0:15], v[44:47], v[48:51], v[0:15]
	v_lshl_or_b32 v48, v60, 16, v59
	v_lshl_or_b32 v49, v62, 16, v61
	v_lshl_or_b32 v50, v64, 16, v63
	v_lshl_or_b32 v51, v66, 16, v65
	ds_read_u16 v56, v43 offset:13600
	ds_read_u16 v57, v43 offset:13872
	ds_read_u16 v58, v43 offset:14144
	ds_read_u16 v59, v43 offset:14416
	v_mfma_f32_32x32x16_bf16 v[16:31], v[44:47], v[48:51], v[16:31]
	v_lshl_or_b32 v44, v76, 16, v75
	v_lshl_or_b32 v45, v78, 16, v77
	v_lshl_or_b32 v46, v80, 16, v79
	v_lshl_or_b32 v47, v82, 16, v81
	v_lshl_or_b32 v48, v92, 16, v91
	s_waitcnt lgkmcnt(14)
	v_lshl_or_b32 v49, v94, 16, v93
	v_lshl_or_b32 v50, v96, 16, v95
	v_mfma_f32_32x32x16_bf16 v[0:15], v[52:55], v[44:47], v[0:15]
	v_lshl_or_b32 v51, v98, 16, v97
	v_lshl_or_b32 v44, v84, 16, v83
	v_lshl_or_b32 v45, v86, 16, v85
	v_lshl_or_b32 v46, v88, 16, v87
	v_lshl_or_b32 v47, v90, 16, v89
	s_nop 1
	v_mfma_f32_32x32x16_bf16 v[16:31], v[52:55], v[44:47], v[16:31]
	s_waitcnt lgkmcnt(12)
	v_lshl_or_b32 v44, v100, 16, v99
	s_waitcnt lgkmcnt(10)
	v_lshl_or_b32 v45, v102, 16, v101
	s_waitcnt lgkmcnt(8)
	v_lshl_or_b32 v46, v104, 16, v103
	s_waitcnt lgkmcnt(6)
	v_lshl_or_b32 v47, v106, 16, v105
	s_nop 1
	v_mfma_f32_32x32x16_bf16 v[0:15], v[48:51], v[44:47], v[0:15]
	ds_read_u16 v47, v43 offset:14688
	ds_read_u16 v52, v43 offset:14960
	s_waitcnt lgkmcnt(6)
	v_lshl_or_b32 v44, v108, 16, v107
	s_waitcnt lgkmcnt(4)
	v_lshl_or_b32 v45, v57, 16, v56
	s_waitcnt lgkmcnt(2)
	v_lshl_or_b32 v46, v59, 16, v58
	s_waitcnt lgkmcnt(0)
	v_lshl_or_b32 v47, v52, 16, v47
	s_nop 1
	v_cvt_pk_bf16_f32 v0, v0, s0
	v_mfma_f32_32x32x16_bf16 v[16:31], v[48:51], v[44:47], v[16:31]
	v_cvt_pk_bf16_f32 v1, v1, s0
	v_cvt_pk_bf16_f32 v2, v2, s0
	v_cvt_pk_bf16_f32 v3, v3, s0
	v_cvt_pk_bf16_f32 v4, v4, s0
	v_cvt_pk_bf16_f32 v5, v5, s0
	v_cvt_pk_bf16_f32 v6, v6, s0
	v_cvt_pk_bf16_f32 v7, v7, s0
	s_nop 4
	v_cvt_pk_bf16_f32 v16, v16, s0
	v_cvt_pk_bf16_f32 v17, v17, s0
	v_cvt_pk_bf16_f32 v18, v18, s0
	v_cvt_pk_bf16_f32 v19, v19, s0
	v_cvt_pk_bf16_f32 v20, v20, s0
	v_cvt_pk_bf16_f32 v21, v21, s0
	v_cvt_pk_bf16_f32 v22, v22, s0
	v_cvt_pk_bf16_f32 v23, v23, s0
	v_cvt_pk_bf16_f32 v8, v8, s0
	v_cvt_pk_bf16_f32 v24, v24, s0
	v_cvt_pk_bf16_f32 v9, v9, s0
	v_cvt_pk_bf16_f32 v25, v25, s0
	v_cvt_pk_bf16_f32 v10, v10, s0
	v_cvt_pk_bf16_f32 v26, v26, s0
	v_cvt_pk_bf16_f32 v11, v11, s0
	v_cvt_pk_bf16_f32 v27, v27, s0
	v_cvt_pk_bf16_f32 v12, v12, s0
	v_cvt_pk_bf16_f32 v28, v28, s0
	v_cvt_pk_bf16_f32 v13, v13, s0
	v_cvt_pk_bf16_f32 v29, v29, s0
	v_cvt_pk_bf16_f32 v14, v14, s0
	v_cvt_pk_bf16_f32 v30, v30, s0
	v_cvt_pk_bf16_f32 v15, v15, s0
	v_cvt_pk_bf16_f32 v31, v31, s0
	global_store_short v[36:37], v0, off offset:-2880
	global_store_short v[36:37], v16, off offset:-2816
	global_store_short v[36:37], v1, off offset:-2624
	global_store_short v[36:37], v17, off offset:-2560
	global_store_short v[36:37], v2, off offset:-2368
	global_store_short v[36:37], v18, off offset:-2304
	global_store_short v[36:37], v3, off offset:-2112
	global_store_short v[36:37], v19, off offset:-2048
	global_store_short v[36:37], v4, off offset:-832
	global_store_short v[36:37], v20, off offset:-768
	global_store_short v[36:37], v5, off offset:-576
	global_store_short v[36:37], v21, off offset:-512
	global_store_short v[36:37], v6, off offset:-320
	global_store_short v[36:37], v22, off offset:-256
	global_store_short v[36:37], v7, off offset:-64
	global_store_short v[34:35], v23, off offset:-4096
	global_store_short v[34:35], v8, off offset:-2880
	global_store_short v[34:35], v24, off offset:-2816
	global_store_short v[34:35], v9, off offset:-2624
	global_store_short v[34:35], v25, off offset:-2560
	global_store_short v[34:35], v10, off offset:-2368
	global_store_short v[34:35], v26, off offset:-2304
	global_store_short v[34:35], v11, off offset:-2112
	global_store_short v[34:35], v27, off offset:-2048
	global_store_short v[34:35], v12, off offset:-832
	global_store_short v[34:35], v28, off offset:-768
	global_store_short v[34:35], v13, off offset:-576
	global_store_short v[34:35], v29, off offset:-512
	global_store_short v[34:35], v14, off offset:-320
	global_store_short v[34:35], v30, off offset:-256
	global_store_short v[34:35], v15, off offset:-64
	global_store_short v[34:35], v31, off
	s_waitcnt lgkmcnt(0)
	s_barrier
	v_lshl_add_u64 v[34:35], v[34:35], 0, s[34:35]
	s_cmp_lg_u32 s16, 0
	s_cbranch_scc1 .LBB0_464
